# RWKV scan: next chunk's raw inputs brought into LDS by LDS-DMA from the four idle waves during the step loop (no register prefetch / LDS write-back on the step waves)
# speedup vs baseline: 1.0364x; 1.0044x over previous
.LBB0_1454:
	s_and_b64 vcc, exec, s[4:5]
	s_cbranch_vccz .LBB0_1563
	s_add_u32 s82, s8, 0x2ea00000
	s_load_dwordx4 s[40:43], s[6:7], 0x70
	s_load_dwordx2 s[74:75], s[6:7], 0x88
	s_load_dwordx8 s[20:27], s[6:7], 0xa0
	s_load_dwordx2 s[72:73], s[6:7], 0xc0
	s_mul_hi_i32 s0, s16, 0x2aaaaaab
	s_addc_u32 s83, s9, 0
	s_lshr_b32 s1, s0, 31
	s_ashr_i32 s0, s0, 2
	s_add_i32 s0, s0, s1
	s_mul_i32 s1, s0, 0xffffffe8
	s_add_i32 s2, s1, s16
	s_ashr_i32 s1, s0, 31
	s_lshl_b64 s[34:35], s[0:1], 11
	v_and_b32_e32 v29, 15, v162
	s_lshl_b32 s76, s2, 6
	s_waitcnt vmcnt(0)
	v_add_u32_e32 v0, 0xffffffa0, v162
	s_movk_i32 s0, 0xc00
	v_mov_b32_e32 v3, 0
	v_lshlrev_b32_e32 v31, 2, v29
	s_ashr_i32 s77, s76, 31
	s_cmp_lt_u32 s78, 4
	s_cbranch_scc1 .Lrwdma_setup_done
	s_add_u32 s92, s8, 0x18a00000
	s_addc_u32 s93, s9, 0
	s_lshl_b32 s94, s76, 2
	s_sub_i32 s95, s78, 4
	s_lshl_b32 s95, s95, 10
	s_add_i32 s95, s95, s47
	s_add_i32 s95, s95, 0x10100
	s_mov_b64 s[96:97], 0
	s_cmp_eq_u32 s78, 4
	s_cselect_b32 s96, -1, 0
	s_cselect_b32 s97, -1, 0
	s_cmp_eq_u32 s78, 5
	s_cselect_b32 s96, -1, s96
	v_mov_b32_e32 v253, 0
	v_add_u32_e32 v246, -256, v240
	v_mul_u32_u24_e32 v247, 0xaaab, v246
	v_lshrrev_b32_e32 v247, 22, v247
	v_mul_u32_u24_e32 v248, 0x60, v247
	v_sub_u32_e32 v248, v246, v248
	v_lshrrev_b32_e32 v249, 4, v248
	v_and_b32_e32 v250, 15, v248
	v_cmp_lt_u32_e32 vcc, 2, v249
	v_mov_b32_e32 v251, 0x5800
	v_mov_b32_e32 v252, 0x4800
	v_cndmask_b32_e32 v251, v251, v252, vcc
	v_add_u32_e32 v252, -3, v249
	v_cndmask_b32_e32 v249, v249, v252, vcc
	v_mul_u32_u24_e32 v252, 0x1800, v249
	v_lshl_add_u32 v252, v250, 4, v252
	v_add_u32_e32 v252, s94, v252
	v_mov_b32_e32 v180, s92
	v_mov_b32_e32 v248, s82
	v_cndmask_b32_e32 v180, v180, v248, vcc
	v_mov_b32_e32 v181, s93
	v_mov_b32_e32 v248, s83
	v_cndmask_b32_e32 v181, v181, v248, vcc
	v_add_u32_e32 v247, s34, v247
	v_add_u32_e32 v247, 31, v247
	v_mad_u64_u32 v[180:181], vcc, v247, v251, v[180:181]
	v_lshl_add_u64 v[180:181], v[180:181], 0, v[252:253]
	v_lshlrev_b32_e32 v208, 5, v251
	v_mov_b32_e32 v209, 0
	v_add_u32_e32 v246, 0, v240
	v_mul_u32_u24_e32 v247, 0xaaab, v246
	v_lshrrev_b32_e32 v247, 22, v247
	v_mul_u32_u24_e32 v248, 0x60, v247
	v_sub_u32_e32 v248, v246, v248
	v_lshrrev_b32_e32 v249, 4, v248
	v_and_b32_e32 v250, 15, v248
	v_cmp_lt_u32_e32 vcc, 2, v249
	v_mov_b32_e32 v251, 0x5800
	v_mov_b32_e32 v252, 0x4800
	v_cndmask_b32_e32 v251, v251, v252, vcc
	v_add_u32_e32 v252, -3, v249
	v_cndmask_b32_e32 v249, v249, v252, vcc
	v_mul_u32_u24_e32 v252, 0x1800, v249
	v_lshl_add_u32 v252, v250, 4, v252
	v_add_u32_e32 v252, s94, v252
	v_mov_b32_e32 v182, s92
	v_mov_b32_e32 v248, s82
	v_cndmask_b32_e32 v182, v182, v248, vcc
	v_mov_b32_e32 v183, s93
	v_mov_b32_e32 v248, s83
	v_cndmask_b32_e32 v183, v183, v248, vcc
	v_add_u32_e32 v247, s34, v247
	v_add_u32_e32 v247, 31, v247
	v_mad_u64_u32 v[182:183], vcc, v247, v251, v[182:183]
	v_lshl_add_u64 v[182:183], v[182:183], 0, v[252:253]
	v_lshlrev_b32_e32 v210, 5, v251
	v_mov_b32_e32 v211, 0
	v_add_u32_e32 v246, 256, v240
	v_mul_u32_u24_e32 v247, 0xaaab, v246
	v_lshrrev_b32_e32 v247, 22, v247
	v_mul_u32_u24_e32 v248, 0x60, v247
	v_sub_u32_e32 v248, v246, v248
	v_lshrrev_b32_e32 v249, 4, v248
	v_and_b32_e32 v250, 15, v248
	v_cmp_lt_u32_e32 vcc, 2, v249
	v_mov_b32_e32 v251, 0x5800
	v_mov_b32_e32 v252, 0x4800
	v_cndmask_b32_e32 v251, v251, v252, vcc
	v_add_u32_e32 v252, -3, v249
	v_cndmask_b32_e32 v249, v249, v252, vcc
	v_mul_u32_u24_e32 v252, 0x1800, v249
	v_lshl_add_u32 v252, v250, 4, v252
	v_add_u32_e32 v252, s94, v252
	v_mov_b32_e32 v184, s92
	v_mov_b32_e32 v248, s82
	v_cndmask_b32_e32 v184, v184, v248, vcc
	v_mov_b32_e32 v185, s93
	v_mov_b32_e32 v248, s83
	v_cndmask_b32_e32 v185, v185, v248, vcc
	v_add_u32_e32 v247, s34, v247
	v_add_u32_e32 v247, 31, v247
	v_mad_u64_u32 v[184:185], vcc, v247, v251, v[184:185]
	v_lshl_add_u64 v[184:185], v[184:185], 0, v[252:253]
	v_lshlrev_b32_e32 v212, 5, v251
	v_mov_b32_e32 v213, 0
	v_add_u32_e32 v246, 512, v240
	v_mul_u32_u24_e32 v247, 0xaaab, v246
	v_lshrrev_b32_e32 v247, 22, v247
	v_mul_u32_u24_e32 v248, 0x60, v247
	v_sub_u32_e32 v248, v246, v248
	v_lshrrev_b32_e32 v249, 4, v248
	v_and_b32_e32 v250, 15, v248
	v_cmp_lt_u32_e32 vcc, 2, v249
	v_mov_b32_e32 v251, 0x5800
	v_mov_b32_e32 v252, 0x4800
	v_cndmask_b32_e32 v251, v251, v252, vcc
	v_add_u32_e32 v252, -3, v249
	v_cndmask_b32_e32 v249, v249, v252, vcc
	v_mul_u32_u24_e32 v252, 0x1800, v249
	v_lshl_add_u32 v252, v250, 4, v252
	v_add_u32_e32 v252, s94, v252
	v_mov_b32_e32 v186, s92
	v_mov_b32_e32 v248, s82
	v_cndmask_b32_e32 v186, v186, v248, vcc
	v_mov_b32_e32 v187, s93
	v_mov_b32_e32 v248, s83
	v_cndmask_b32_e32 v187, v187, v248, vcc
	v_add_u32_e32 v247, s34, v247
	v_add_u32_e32 v247, 31, v247
	v_mad_u64_u32 v[186:187], vcc, v247, v251, v[186:187]
	v_lshl_add_u64 v[186:187], v[186:187], 0, v[252:253]
	v_lshlrev_b32_e32 v214, 5, v251
	v_mov_b32_e32 v215, 0
	v_add_u32_e32 v246, 768, v240
	v_mul_u32_u24_e32 v247, 0xaaab, v246
	v_lshrrev_b32_e32 v247, 22, v247
	v_mul_u32_u24_e32 v248, 0x60, v247
	v_sub_u32_e32 v248, v246, v248
	v_lshrrev_b32_e32 v249, 4, v248
	v_and_b32_e32 v250, 15, v248
	v_cmp_lt_u32_e32 vcc, 2, v249
	v_mov_b32_e32 v251, 0x5800
	v_mov_b32_e32 v252, 0x4800
	v_cndmask_b32_e32 v251, v251, v252, vcc
	v_add_u32_e32 v252, -3, v249
	v_cndmask_b32_e32 v249, v249, v252, vcc
	v_mul_u32_u24_e32 v252, 0x1800, v249
	v_lshl_add_u32 v252, v250, 4, v252
	v_add_u32_e32 v252, s94, v252
	v_mov_b32_e32 v188, s92
	v_mov_b32_e32 v248, s82
	v_cndmask_b32_e32 v188, v188, v248, vcc
	v_mov_b32_e32 v189, s93
	v_mov_b32_e32 v248, s83
	v_cndmask_b32_e32 v189, v189, v248, vcc
	v_add_u32_e32 v247, s34, v247
	v_add_u32_e32 v247, 31, v247
	v_mad_u64_u32 v[188:189], vcc, v247, v251, v[188:189]
	v_lshl_add_u64 v[188:189], v[188:189], 0, v[252:253]
	v_lshlrev_b32_e32 v216, 5, v251
	v_mov_b32_e32 v217, 0
	v_add_u32_e32 v246, 1024, v240
	v_mul_u32_u24_e32 v247, 0xaaab, v246
	v_lshrrev_b32_e32 v247, 22, v247
	v_mul_u32_u24_e32 v248, 0x60, v247
	v_sub_u32_e32 v248, v246, v248
	v_lshrrev_b32_e32 v249, 4, v248
	v_and_b32_e32 v250, 15, v248
	v_cmp_lt_u32_e32 vcc, 2, v249
	v_mov_b32_e32 v251, 0x5800
	v_mov_b32_e32 v252, 0x4800
	v_cndmask_b32_e32 v251, v251, v252, vcc
	v_add_u32_e32 v252, -3, v249
	v_cndmask_b32_e32 v249, v249, v252, vcc
	v_mul_u32_u24_e32 v252, 0x1800, v249
	v_lshl_add_u32 v252, v250, 4, v252
	v_add_u32_e32 v252, s94, v252
	v_mov_b32_e32 v190, s92
	v_mov_b32_e32 v248, s82
	v_cndmask_b32_e32 v190, v190, v248, vcc
	v_mov_b32_e32 v191, s93
	v_mov_b32_e32 v248, s83
	v_cndmask_b32_e32 v191, v191, v248, vcc
	v_add_u32_e32 v247, s34, v247
	v_add_u32_e32 v247, 31, v247
	v_mad_u64_u32 v[190:191], vcc, v247, v251, v[190:191]
	v_lshl_add_u64 v[190:191], v[190:191], 0, v[252:253]
	v_lshlrev_b32_e32 v218, 5, v251
	v_mov_b32_e32 v219, 0
	v_add_u32_e32 v246, 1280, v240
	v_mul_u32_u24_e32 v247, 0xaaab, v246
	v_lshrrev_b32_e32 v247, 22, v247
	v_mul_u32_u24_e32 v248, 0x60, v247
	v_sub_u32_e32 v248, v246, v248
	v_lshrrev_b32_e32 v249, 4, v248
	v_and_b32_e32 v250, 15, v248
	v_cmp_lt_u32_e32 vcc, 2, v249
	v_mov_b32_e32 v251, 0x5800
	v_mov_b32_e32 v252, 0x4800
	v_cndmask_b32_e32 v251, v251, v252, vcc
	v_add_u32_e32 v252, -3, v249
	v_cndmask_b32_e32 v249, v249, v252, vcc
	v_mul_u32_u24_e32 v252, 0x1800, v249
	v_lshl_add_u32 v252, v250, 4, v252
	v_add_u32_e32 v252, s94, v252
	v_mov_b32_e32 v192, s92
	v_mov_b32_e32 v248, s82
	v_cndmask_b32_e32 v192, v192, v248, vcc
	v_mov_b32_e32 v193, s93
	v_mov_b32_e32 v248, s83
	v_cndmask_b32_e32 v193, v193, v248, vcc
	v_add_u32_e32 v247, s34, v247
	v_add_u32_e32 v247, 31, v247
	v_mad_u64_u32 v[192:193], vcc, v247, v251, v[192:193]
	v_lshl_add_u64 v[192:193], v[192:193], 0, v[252:253]
	v_lshlrev_b32_e32 v220, 5, v251
	v_mov_b32_e32 v221, 0
	v_add_u32_e32 v246, 1536, v240
	v_mul_u32_u24_e32 v247, 0xaaab, v246
	v_lshrrev_b32_e32 v247, 22, v247
	v_mul_u32_u24_e32 v248, 0x60, v247
	v_sub_u32_e32 v248, v246, v248
	v_lshrrev_b32_e32 v249, 4, v248
	v_and_b32_e32 v250, 15, v248
	v_cmp_lt_u32_e32 vcc, 2, v249
	v_mov_b32_e32 v251, 0x5800
	v_mov_b32_e32 v252, 0x4800
	v_cndmask_b32_e32 v251, v251, v252, vcc
	v_add_u32_e32 v252, -3, v249
	v_cndmask_b32_e32 v249, v249, v252, vcc
	v_mul_u32_u24_e32 v252, 0x1800, v249
	v_lshl_add_u32 v252, v250, 4, v252
	v_add_u32_e32 v252, s94, v252
	v_mov_b32_e32 v194, s92
	v_mov_b32_e32 v248, s82
	v_cndmask_b32_e32 v194, v194, v248, vcc
	v_mov_b32_e32 v195, s93
	v_mov_b32_e32 v248, s83
	v_cndmask_b32_e32 v195, v195, v248, vcc
	v_add_u32_e32 v247, s34, v247
	v_add_u32_e32 v247, 31, v247
	v_mad_u64_u32 v[194:195], vcc, v247, v251, v[194:195]
	v_lshl_add_u64 v[194:195], v[194:195], 0, v[252:253]
	v_lshlrev_b32_e32 v222, 5, v251
	v_mov_b32_e32 v223, 0
	v_add_u32_e32 v246, 1792, v240
	v_mul_u32_u24_e32 v247, 0xaaab, v246
	v_lshrrev_b32_e32 v247, 22, v247
	v_mul_u32_u24_e32 v248, 0x60, v247
	v_sub_u32_e32 v248, v246, v248
	v_lshrrev_b32_e32 v249, 4, v248
	v_and_b32_e32 v250, 15, v248
	v_cmp_lt_u32_e32 vcc, 2, v249
	v_mov_b32_e32 v251, 0x5800
	v_mov_b32_e32 v252, 0x4800
	v_cndmask_b32_e32 v251, v251, v252, vcc
	v_add_u32_e32 v252, -3, v249
	v_cndmask_b32_e32 v249, v249, v252, vcc
	v_mul_u32_u24_e32 v252, 0x1800, v249
	v_lshl_add_u32 v252, v250, 4, v252
	v_add_u32_e32 v252, s94, v252
	v_mov_b32_e32 v196, s92
	v_mov_b32_e32 v248, s82
	v_cndmask_b32_e32 v196, v196, v248, vcc
	v_mov_b32_e32 v197, s93
	v_mov_b32_e32 v248, s83
	v_cndmask_b32_e32 v197, v197, v248, vcc
	v_add_u32_e32 v247, s34, v247
	v_add_u32_e32 v247, 31, v247
	v_mad_u64_u32 v[196:197], vcc, v247, v251, v[196:197]
	v_lshl_add_u64 v[196:197], v[196:197], 0, v[252:253]
	v_lshlrev_b32_e32 v224, 5, v251
	v_mov_b32_e32 v225, 0
	v_add_u32_e32 v246, 2048, v240
	v_mul_u32_u24_e32 v247, 0xaaab, v246
	v_lshrrev_b32_e32 v247, 22, v247
	v_mul_u32_u24_e32 v248, 0x60, v247
	v_sub_u32_e32 v248, v246, v248
	v_lshrrev_b32_e32 v249, 4, v248
	v_and_b32_e32 v250, 15, v248
	v_cmp_lt_u32_e32 vcc, 2, v249
	v_mov_b32_e32 v251, 0x5800
	v_mov_b32_e32 v252, 0x4800
	v_cndmask_b32_e32 v251, v251, v252, vcc
	v_add_u32_e32 v252, -3, v249
	v_cndmask_b32_e32 v249, v249, v252, vcc
	v_mul_u32_u24_e32 v252, 0x1800, v249
	v_lshl_add_u32 v252, v250, 4, v252
	v_add_u32_e32 v252, s94, v252
	v_mov_b32_e32 v198, s92
	v_mov_b32_e32 v248, s82
	v_cndmask_b32_e32 v198, v198, v248, vcc
	v_mov_b32_e32 v199, s93
	v_mov_b32_e32 v248, s83
	v_cndmask_b32_e32 v199, v199, v248, vcc
	v_add_u32_e32 v247, s34, v247
	v_add_u32_e32 v247, 31, v247
	v_mad_u64_u32 v[198:199], vcc, v247, v251, v[198:199]
	v_lshl_add_u64 v[198:199], v[198:199], 0, v[252:253]
	v_lshlrev_b32_e32 v226, 5, v251
	v_mov_b32_e32 v227, 0
	v_add_u32_e32 v246, 2304, v240
	v_mul_u32_u24_e32 v247, 0xaaab, v246
	v_lshrrev_b32_e32 v247, 22, v247
	v_mul_u32_u24_e32 v248, 0x60, v247
	v_sub_u32_e32 v248, v246, v248
	v_lshrrev_b32_e32 v249, 4, v248
	v_and_b32_e32 v250, 15, v248
	v_cmp_lt_u32_e32 vcc, 2, v249
	v_mov_b32_e32 v251, 0x5800
	v_mov_b32_e32 v252, 0x4800
	v_cndmask_b32_e32 v251, v251, v252, vcc
	v_add_u32_e32 v252, -3, v249
	v_cndmask_b32_e32 v249, v249, v252, vcc
	v_mul_u32_u24_e32 v252, 0x1800, v249
	v_lshl_add_u32 v252, v250, 4, v252
	v_add_u32_e32 v252, s94, v252
	v_mov_b32_e32 v200, s92
	v_mov_b32_e32 v248, s82
	v_cndmask_b32_e32 v200, v200, v248, vcc
	v_mov_b32_e32 v201, s93
	v_mov_b32_e32 v248, s83
	v_cndmask_b32_e32 v201, v201, v248, vcc
	v_add_u32_e32 v247, s34, v247
	v_add_u32_e32 v247, 31, v247
	v_mad_u64_u32 v[200:201], vcc, v247, v251, v[200:201]
	v_lshl_add_u64 v[200:201], v[200:201], 0, v[252:253]
	v_lshlrev_b32_e32 v228, 5, v251
	v_mov_b32_e32 v229, 0
	v_add_u32_e32 v246, 2560, v240
	v_mul_u32_u24_e32 v247, 0xaaab, v246
	v_lshrrev_b32_e32 v247, 22, v247
	v_mul_u32_u24_e32 v248, 0x60, v247
	v_sub_u32_e32 v248, v246, v248
	v_lshrrev_b32_e32 v249, 4, v248
	v_and_b32_e32 v250, 15, v248
	v_cmp_lt_u32_e32 vcc, 2, v249
	v_mov_b32_e32 v251, 0x5800
	v_mov_b32_e32 v252, 0x4800
	v_cndmask_b32_e32 v251, v251, v252, vcc
	v_add_u32_e32 v252, -3, v249
	v_cndmask_b32_e32 v249, v249, v252, vcc
	v_mul_u32_u24_e32 v252, 0x1800, v249
	v_lshl_add_u32 v252, v250, 4, v252
	v_add_u32_e32 v252, s94, v252
	v_mov_b32_e32 v202, s92
	v_mov_b32_e32 v248, s82
	v_cndmask_b32_e32 v202, v202, v248, vcc
	v_mov_b32_e32 v203, s93
	v_mov_b32_e32 v248, s83
	v_cndmask_b32_e32 v203, v203, v248, vcc
	v_add_u32_e32 v247, s34, v247
	v_add_u32_e32 v247, 31, v247
	v_mad_u64_u32 v[202:203], vcc, v247, v251, v[202:203]
	v_lshl_add_u64 v[202:203], v[202:203], 0, v[252:253]
	v_lshlrev_b32_e32 v230, 5, v251
	v_mov_b32_e32 v231, 0
	v_add_u32_e32 v246, 2816, v240
	v_mul_u32_u24_e32 v247, 0xaaab, v246
	v_lshrrev_b32_e32 v247, 22, v247
	v_mul_u32_u24_e32 v248, 0x60, v247
	v_sub_u32_e32 v248, v246, v248
	v_lshrrev_b32_e32 v249, 4, v248
	v_and_b32_e32 v250, 15, v248
	v_cmp_lt_u32_e32 vcc, 2, v249
	v_mov_b32_e32 v251, 0x5800
	v_mov_b32_e32 v252, 0x4800
	v_cndmask_b32_e32 v251, v251, v252, vcc
	v_add_u32_e32 v252, -3, v249
	v_cndmask_b32_e32 v249, v249, v252, vcc
	v_mul_u32_u24_e32 v252, 0x1800, v249
	v_lshl_add_u32 v252, v250, 4, v252
	v_add_u32_e32 v252, s94, v252
	v_mov_b32_e32 v204, s92
	v_mov_b32_e32 v248, s82
	v_cndmask_b32_e32 v204, v204, v248, vcc
	v_mov_b32_e32 v205, s93
	v_mov_b32_e32 v248, s83
	v_cndmask_b32_e32 v205, v205, v248, vcc
	v_add_u32_e32 v247, s34, v247
	v_add_u32_e32 v247, 31, v247
	v_mad_u64_u32 v[204:205], vcc, v247, v251, v[204:205]
	v_lshl_add_u64 v[204:205], v[204:205], 0, v[252:253]
	v_lshlrev_b32_e32 v232, 5, v251
	v_mov_b32_e32 v233, 0
.Lrwdma_setup_done:
	v_cmp_gt_u32_e32 vcc, s0, v0
	v_mov_b32_e32 v2, v3
	v_mov_b32_e32 v1, v3
	v_mov_b32_e32 v0, v3
	s_and_saveexec_b64 s[4:5], vcc
	s_cbranch_execz .LBB0_1461
	v_mul_u32_u24_e32 v0, 0xaaab, v162
	v_lshrrev_b32_e32 v0, 22, v0
	s_movk_i32 s0, 0xffa0
	v_mad_i32_i24 v1, v0, s0, v162
	v_ashrrev_i32_e32 v1, 4, v1
	v_add_u32_e32 v128, -1, v0
	s_movk_i32 s0, 0x600
	v_lshl_add_u64 v[2:3], s[34:35], 0, v[128:129]
	v_cmp_lt_i32_e32 vcc, 2, v1
	v_mul_lo_u32 v0, v1, s0
	s_and_saveexec_b64 s[0:1], vcc
	s_xor_b64 s[6:7], exec, s[0:1]
	v_mov_b64_e32 v[4:5], s[82:83]
	s_movk_i32 s2, 0x4800
	v_mad_u64_u32 v[4:5], s[0:1], v2, s2, v[4:5]
	v_mad_i32_i24 v5, v3, s2, v5
	v_mov_b32_e32 v1, v129
	s_movk_i32 s0, 0xb800
	v_lshl_add_u64 v[0:1], v[0:1], 2, v[4:5]
	s_mov_b32 s1, -1
	v_lshl_add_u64 v[4:5], v[0:1], 0, s[0:1]
	s_andn2_saveexec_b64 s[6:7], s[6:7]
	v_mov_b64_e32 v[4:5], s[18:19]
	s_movk_i32 s2, 0x5800
	v_mad_u64_u32 v[4:5], s[0:1], v2, s2, v[4:5]
	v_mad_i32_i24 v5, v3, s2, v5
	v_ashrrev_i32_e32 v1, 31, v0
	v_lshl_add_u64 v[4:5], v[0:1], 2, v[4:5]
	s_or_b64 exec, exec, s[6:7]
	v_lshl_add_u64 v[0:1], s[76:77], 2, v[4:5]
	v_lshlrev_b32_e32 v128, 2, v31
	v_lshl_add_u64 v[0:1], v[0:1], 0, v[128:129]
	global_load_dwordx4 v[0:3], v[0:1], off

; #define LAS __attribute__((address_space(3)))
; DI unsigned pk2(float lo, float hi) { f32x2 v = {lo, hi}; bf16x2_t b = __builtin_convertvector(v, bf16x2_t); return __builtin_bit_cast(unsigned, b); }
; DI float red16(float v) { v += dppf<0xB1>(v); v += dppf<0x4E>(v); v += dppf<0x141>(v); v += dppf<0x128>(v); return v; }
; DI float dot4(f32x4 a, f32x4 b) { return (a.x * b.x + a.y * b.y) + (a.z * b.z + a.w * b.w); }
; DI float frsq(float x) { return __builtin_amdgcn_rsqf(x); }
; DI void lds_barrier() { asm volatile("s_waitcnt lgkmcnt(0)" ::: "memory"); __builtin_amdgcn_s_barrier(); asm volatile("" ::: "memory"); }
; DI void rwkv_scan_block(LAS unsigned char* lds, int c, const float* P, const float* LO, const RwkvPar& pr, bf16* YCAT, int tid, int lane, int wave) {
;     ...
;         lds_barrier();
;         {
;             const f32x4 y4 = *(const LAS f32x4*)(Y_ + dt * 64 + k4);
;             const float mean = red16((y4.x + y4.y) + (y4.z + y4.w)) * (1.f / 64.f);
;             const f32x4 d = y4 - mean;
;             const float var = red16(dot4(d, d)) * (1.f / 64.f);
;             const f32x4 yn = d * (frsq(var + 64e-5f)) * *(const f32x4*)(pr.gn_g + ch) + *(const f32x4*)(pr.gn_b + ch);
;             const f32x4 o = (yn + BS_[dt] * *(const LAS f32x4*)(V_ + dt * 64 + k4)) * *(const LAS f32x4*)(G_ + dt * 64 + k4);
;             u32x2 w; w.x = pk2(o.x, o.y); w.y = pk2(o.z, o.w);
;             *(u32x2*)(YCAT + (tok_base + cidx * 32 + dt) * DM + ch) = w;
;         }
.LBB0_1498:
	s_waitcnt lgkmcnt(0)
	s_waitcnt vmcnt(0)
	s_barrier
	s_waitcnt lgkmcnt(2)
	ds_read_b128 v[36:39], v109 offset:57344
	s_lshl_b32 s46, s0, 5
	s_cmp_eq_u32 s1, 64
	s_mov_b32 s0, s1
	s_waitcnt lgkmcnt(0)
	v_mov_b32_e32 v40, v37
	v_mov_b32_e32 v41, v38
	v_mov_b32_e32 v42, v36
	v_mov_b32_e32 v43, v39
	v_pk_add_f32 v[40:41], v[40:41], v[42:43]
	s_nop 0
	v_add_f32_e32 v40, v40, v41
	s_nop 1
	v_add_f32_dpp v40, v40, v40 quad_perm:[1,0,3,2] row_mask:0xf bank_mask:0xf bound_ctrl:1
	s_nop 1
	v_add_f32_dpp v40, v40, v40 quad_perm:[2,3,0,1] row_mask:0xf bank_mask:0xf bound_ctrl:1
	s_nop 1
	v_add_f32_dpp v40, v40, v40 row_half_mirror row_mask:0xf bank_mask:0xf bound_ctrl:1
	s_nop 1
	v_add_f32_dpp v40, v40, v40 row_ror:8 row_mask:0xf bank_mask:0xf bound_ctrl:1
	v_fmamk_f32 v37, v40, 0xbc800000, v37
	v_fmamk_f32 v36, v40, 0xbc800000, v36
	v_fmamk_f32 v39, v40, 0xbc800000, v39
	v_fmac_f32_e32 v38, 0xbc800000, v40
	v_pk_mul_f32 v[40:41], v[38:39], v[38:39]
	v_pk_mul_f32 v[42:43], v[36:37], v[36:37]
	s_nop 0
	v_pk_mov_b32 v[44:45], v[42:43], v[40:41] op_sel:[1,0]
	v_mov_b32_e32 v43, v41
	v_pk_add_f32 v[40:41], v[44:45], v[42:43]
	s_nop 0
	v_add_f32_e32 v40, v40, v41
	v_mov_b32_e32 v41, 0x3a27c5ac
	s_nop 0
	v_add_f32_dpp v40, v40, v40 quad_perm:[1,0,3,2] row_mask:0xf bank_mask:0xf bound_ctrl:1
	s_nop 1
	v_add_f32_dpp v40, v40, v40 quad_perm:[2,3,0,1] row_mask:0xf bank_mask:0xf bound_ctrl:1
	s_nop 1
	v_add_f32_dpp v40, v40, v40 row_half_mirror row_mask:0xf bank_mask:0xf bound_ctrl:1
	s_nop 1
	v_add_f32_dpp v40, v40, v40 row_ror:8 row_mask:0xf bank_mask:0xf bound_ctrl:1
	v_fmamk_f32 v40, v40, 0x3c800000, v41
	v_rsq_f32_e32 v40, v40
	s_nop 0
	v_pk_mul_f32 v[44:45], v[36:37], v[40:41] op_sel_hi:[1,0]
	v_pk_mul_f32 v[46:47], v[38:39], v[40:41] op_sel_hi:[1,0]
	ds_read_b128 v[36:39], v234 offset:2048
	ds_read_b128 v[40:43], v234 offset:2304
	s_waitcnt lgkmcnt(0)
	v_pk_fma_f32 v[42:43], v[38:39], v[46:47], v[42:43]
	v_pk_fma_f32 v[40:41], v[36:37], v[44:45], v[40:41]
	ds_read_b32 v44, v113
	ds_read_b128 v[36:39], v109 offset:24576
	s_waitcnt lgkmcnt(0)
	v_pk_fma_f32 v[40:41], v[36:37], v[44:45], v[40:41] op_sel_hi:[1,0,1]
	v_pk_fma_f32 v[42:43], v[38:39], v[44:45], v[42:43] op_sel_hi:[1,0,1]
	ds_read_b128 v[36:39], v109 offset:49152
	s_waitcnt lgkmcnt(0)
	v_pk_mul_f32 v[38:39], v[38:39], v[42:43]
	v_pk_mul_f32 v[36:37], v[36:37], v[40:41]
	s_nop 0
	v_cvt_pk_bf16_f32 v36, v36, v37
	v_cvt_pk_bf16_f32 v37, v38, v39
	v_lshl_add_u64 v[38:39], v[80:81], 0, s[46:47]
	v_lshlrev_b64 v[38:39], 12, v[38:39]
	v_lshl_add_u64 v[38:39], v[82:83], 0, v[38:39]
	global_store_dwordx2 v[38:39], v[36:37], off
	s_cbranch_scc1 .LBB0_1563
.LBB0_1499:
	s_cmp_lg_u32 s0, 0
	s_cbranch_scc1 .LBB0_1507
	s_and_saveexec_b64 s[18:19], s[14:15]
	s_cbranch_execnz .LBB0_1557
	s_or_b64 exec, exec, s[18:19]
	s_and_saveexec_b64 s[18:19], s[12:13]
	s_cbranch_execnz .LBB0_1558

.LBB0_1507:
	s_or_b64 exec, exec, s[18:19]
	s_waitcnt lgkmcnt(0)
	s_barrier
	ds_read_b128 v[44:47], v234
	ds_read_b128 v[48:51], v234 offset:256
	ds_read_b128 v[40:43], v234 offset:512
	ds_read_b128 v[60:63], v105 offset:1536
	ds_read_b128 v[56:59], v105 offset:1792
	ds_read_b128 v[52:55], v105 offset:2048
	ds_read_b128 v[36:39], v105
	ds_read_b128 v[152:155], v234 offset:1024
	ds_read_b128 v[64:67], v105 offset:2304
	s_mov_b32 s1, 0xbfb8aa3b
	s_mov_b32 s2, 0x800000
	s_waitcnt lgkmcnt(2)
	v_sub_f32_e32 v69, v37, v61
	v_sub_f32_e32 v68, v36, v60
	v_sub_f32_e32 v73, v39, v63
	v_sub_f32_e32 v72, v38, v62
	ds_read_b128 v[36:39], v105 offset:256
	ds_read_b128 v[156:159], v105 offset:2560
	s_mov_b32 s22, 0x3f317217
	s_mov_b32 s23, 0x7f800000
	v_mov_b32_e32 v130, 0x41b17218
	s_waitcnt lgkmcnt(1)
	v_sub_f32_e32 v71, v37, v57
	v_sub_f32_e32 v70, v36, v56
	v_sub_f32_e32 v77, v39, v59
	v_sub_f32_e32 v76, v38, v58
	ds_read_b128 v[36:39], v105 offset:512
	v_mov_b32_e32 v243, 0x41b17218
	s_waitcnt lgkmcnt(0)
	v_sub_f32_e32 v75, v37, v53
	v_sub_f32_e32 v74, v36, v52
	v_sub_f32_e32 v79, v39, v55
	v_sub_f32_e32 v78, v38, v54
	ds_read_b128 v[36:39], v234 offset:768
	v_pk_fma_f32 v[44:45], v[44:45], v[68:69], v[60:61]
	v_pk_fma_f32 v[58:59], v[50:51], v[76:77], v[58:59]
	v_pk_fma_f32 v[56:57], v[48:49], v[70:71], v[56:57]
	ds_read_b128 v[48:51], v234 offset:1280
	v_pk_fma_f32 v[42:43], v[42:43], v[78:79], v[54:55]
	v_pk_fma_f32 v[40:41], v[40:41], v[74:75], v[52:53]
	v_pk_fma_f32 v[46:47], v[46:47], v[72:73], v[62:63]
	s_waitcnt lgkmcnt(1)
	v_add_f32_e32 v36, v36, v64
	v_max_f32_e64 v64, -v36, 0
	v_mul_f32_e64 v36, |v36|, s1
	v_exp_f32_e32 v36, v36
	v_add_f32_e32 v37, v37, v65
	v_max_f32_e64 v65, -v37, 0
	v_mul_f32_e64 v37, |v37|, s1
	v_add_f32_e32 v36, 1.0, v36
	v_cmp_gt_f32_e64 s[18:19], s2, v36
	v_exp_f32_e32 v37, v37
	v_add_f32_e32 v38, v38, v66
	v_cndmask_b32_e64 v128, 0, 32, s[18:19]
	v_ldexp_f32 v36, v36, v128
	v_log_f32_e32 v36, v36
	v_add_f32_e32 v37, 1.0, v37
	v_max_f32_e64 v66, -v38, 0
	v_mul_f32_e64 v38, |v38|, s1
	v_mul_f32_e32 v128, 0x3f317217, v36
	v_fma_f32 v128, v36, s22, -v128
	v_fmac_f32_e32 v128, 0x3377d1cf, v36
	v_fmac_f32_e32 v128, 0x3f317217, v36
	v_cmp_lt_f32_e64 s[20:21], |v36|, s23
	v_exp_f32_e32 v38, v38
	v_add_f32_e32 v39, v39, v67
	v_cndmask_b32_e64 v36, v36, v128, s[20:21]
	v_cndmask_b32_e64 v128, 0, v130, s[18:19]
	v_cmp_gt_f32_e64 s[18:19], s2, v37
	v_sub_f32_e32 v36, v36, v128
	v_add_f32_e32 v38, 1.0, v38
	v_cndmask_b32_e64 v128, 0, 32, s[18:19]
	v_ldexp_f32 v37, v37, v128
	v_log_f32_e32 v37, v37
	v_max_f32_e64 v67, -v39, 0
	v_mul_f32_e64 v39, |v39|, s1
	v_exp_f32_e32 v39, v39
	v_mul_f32_e32 v128, 0x3f317217, v37
	v_fma_f32 v128, v37, s22, -v128
	v_fmac_f32_e32 v128, 0x3377d1cf, v37
	v_fmac_f32_e32 v128, 0x3f317217, v37
	v_cmp_lt_f32_e64 s[20:21], |v37|, s23
	v_add_f32_e32 v39, 1.0, v39
	v_add_f32_e32 v36, v64, v36
	v_cndmask_b32_e64 v37, v37, v128, s[20:21]
	v_cndmask_b32_e64 v128, 0, v130, s[18:19]
	v_cmp_gt_f32_e64 s[18:19], s2, v38
	v_sub_f32_e32 v37, v37, v128
	v_add_f32_e32 v64, v152, v156
	v_cndmask_b32_e64 v128, 0, 32, s[18:19]
	v_ldexp_f32 v38, v38, v128
	v_log_f32_e32 v38, v38
	v_add_f32_e32 v37, v65, v37
	v_add_f32_e32 v65, v153, v157
	v_mul_f32_e32 v64, 0xbfb8aa3b, v64
	s_waitcnt lgkmcnt(0)
	v_pk_mul_f32 v[48:49], v[56:57], v[48:49]
	v_pk_mul_f32 v[50:51], v[58:59], v[50:51]
	v_pk_mul_f32 v[54:55], v[48:49], v[48:49]
	v_pk_mul_f32 v[52:53], v[50:51], v[50:51]
	v_mul_f32_e32 v128, 0x3f317217, v38
	v_pk_mov_b32 v[60:61], v[54:55], v[52:53] op_sel:[1,0]
	v_mov_b32_e32 v55, v53
	v_pk_add_f32 v[52:53], v[60:61], v[54:55]
	v_fma_f32 v128, v38, s22, -v128
	v_add_f32_e32 v52, v52, v53
	v_fmac_f32_e32 v128, 0x3377d1cf, v38
	v_fmac_f32_e32 v128, 0x3f317217, v38
	v_add_f32_dpp v52, v52, v52 quad_perm:[1,0,3,2] row_mask:0xf bank_mask:0xf bound_ctrl:1
	v_cmp_lt_f32_e64 s[20:21], |v38|, s23
	v_mul_f32_e32 v65, 0xbfb8aa3b, v65
	v_add_f32_dpp v52, v52, v52 quad_perm:[2,3,0,1] row_mask:0xf bank_mask:0xf bound_ctrl:1
	v_cndmask_b32_e64 v38, v38, v128, s[20:21]
	v_cndmask_b32_e64 v128, 0, v130, s[18:19]
	v_add_f32_dpp v52, v52, v52 row_half_mirror row_mask:0xf bank_mask:0xf bound_ctrl:1
	v_cmp_gt_f32_e64 s[18:19], s2, v39
	v_sub_f32_e32 v38, v38, v128
	v_add_f32_dpp v52, v52, v52 row_ror:8 row_mask:0xf bank_mask:0xf bound_ctrl:1
	v_add_f32_e32 v52, 0x358637bd, v52
	v_rsq_f32_e32 v52, v52
	v_cndmask_b32_e64 v128, 0, 32, s[18:19]
	v_ldexp_f32 v39, v39, v128
	v_log_f32_e32 v39, v39
	v_pk_mul_f32 v[50:51], v[50:51], v[52:53] op_sel_hi:[1,0]
	v_pk_mul_f32 v[48:49], v[48:49], v[52:53] op_sel_hi:[1,0]
	ds_read_b128 v[52:55], v234 offset:1536
	v_mul_f32_e32 v128, 0x3f317217, v39
	v_fma_f32 v128, v39, s22, -v128
	v_fmac_f32_e32 v128, 0x3377d1cf, v39
	v_fmac_f32_e32 v128, 0x3f317217, v39
	v_cmp_lt_f32_e64 s[20:21], |v39|, s23
	v_add_f32_e32 v38, v66, v38
	v_add_f32_e32 v66, v154, v158
	v_cndmask_b32_e64 v39, v39, v128, s[20:21]
	v_cndmask_b32_e64 v128, 0, v130, s[18:19]
	v_sub_f32_e32 v39, v39, v128
	v_add_f32_e32 v39, v67, v39
	v_add_f32_e32 v67, v155, v159
	v_mul_f32_e32 v66, 0xbfb8aa3b, v66
	v_mul_f32_e32 v67, 0xbfb8aa3b, v67
	v_exp_f32_e32 v64, v64
	v_exp_f32_e32 v65, v65
	v_exp_f32_e32 v66, v66
	v_exp_f32_e32 v67, v67
	v_add_f32_e32 v64, 1.0, v64
	v_add_f32_e32 v65, 1.0, v65
	v_add_f32_e32 v66, 1.0, v66
	v_add_f32_e32 v67, 1.0, v67
	v_rcp_f32_e32 v64, v64
	v_rcp_f32_e32 v65, v65
	v_rcp_f32_e32 v66, v66
	v_rcp_f32_e32 v67, v67
	v_sub_f32_e32 v36, -0.5, v36
	v_pk_add_f32 v[62:63], v[64:65], -1.0 op_sel_hi:[1,0]
	v_sub_f32_e32 v37, -0.5, v37
	v_pk_add_f32 v[60:61], v[66:67], -1.0 op_sel_hi:[1,0]
	v_sub_f32_e32 v38, -0.5, v38
	v_sub_f32_e32 v39, -0.5, v39
	v_mul_f32_e32 v36, 0x3fb8aa3b, v36
	v_mul_f32_e32 v37, 0x3fb8aa3b, v37
	v_mul_f32_e32 v38, 0x3fb8aa3b, v38
	v_mul_f32_e32 v39, 0x3fb8aa3b, v39
	v_exp_f32_e32 v36, v36
	v_exp_f32_e32 v37, v37
	v_exp_f32_e32 v38, v38
	v_exp_f32_e32 v39, v39
	v_mul_f32_e32 v36, 0xbfb8aa3b, v36
	v_mul_f32_e32 v37, 0xbfb8aa3b, v37
	v_mul_f32_e32 v38, 0xbfb8aa3b, v38
	v_mul_f32_e32 v39, 0xbfb8aa3b, v39
	v_exp_f32_e32 v36, v36
	v_exp_f32_e32 v37, v37
	v_exp_f32_e32 v38, v38
	v_exp_f32_e32 v39, v39
	s_waitcnt lgkmcnt(0)
; DI void lds_barrier() { asm volatile("s_waitcnt lgkmcnt(0)" ::: "memory"); __builtin_amdgcn_s_barrier(); asm volatile("" ::: "memory"); }
; #define RW_WRITE() do { _Pragma("unroll") for (int j = 0; j < 7; ++j) { const int e = tid + 512 * j; if (e < 3168) *(LAS f32x4*)(RAW + 4 * e) = pre[j]; } } while (0)
; DI void rwkv_scan_block(LAS unsigned char* lds, int c, const float* P, const float* LO, const RwkvPar& pr, bf16* YCAT, int tid, int lane, int wave) {
;     ...
;     RW_LOAD(0);
; #pragma unroll 1
;     for (int cidx = 0; cidx < 64; ++cidx) {
;         RW_WRITE();
;         lds_barrier();
;         RW_DERIVE();
;         lds_barrier();
;         if (cidx + 1 < 64) RW_LOAD(cidx + 1);
	v_pk_fma_f32 v[52:53], v[52:53], v[62:63], 1.0 op_sel_hi:[1,1,0]
	v_pk_fma_f32 v[54:55], v[54:55], v[60:61], 1.0 op_sel_hi:[1,1,0]
	v_pk_mul_f32 v[52:53], v[56:57], v[52:53]
	v_pk_mul_f32 v[54:55], v[58:59], v[54:55]
	ds_read_b128 v[56:59], v234 offset:1792
	v_pk_mul_f32 v[62:63], v[44:45], v[52:53]
	v_pk_mul_f32 v[60:61], v[46:47], v[54:55]
	ds_write_b128 v109, v[44:47]
	ds_write_b128 v109, v[36:39] offset:8192
	ds_write_b128 v109, v[52:55] offset:16384
	ds_write_b128 v109, v[40:43] offset:24576
	ds_write_b128 v109, v[48:51] offset:32768
	v_pk_mul_f32 v[38:39], v[66:67], v[50:51]
	v_pk_mul_f32 v[36:37], v[64:65], v[48:49]
	ds_write_b128 v109, v[36:39] offset:40960
	ds_read_b128 v[36:39], v105 offset:2816
	s_waitcnt lgkmcnt(0)
	ds_write_b128 v109, v[36:39] offset:49152
	v_mul_f32_e32 v57, v57, v63
	v_fmac_f32_e32 v57, v56, v62
	v_mul_f32_e32 v56, v59, v61
	v_fmac_f32_e32 v56, v58, v60
	v_add_f32_e32 v56, v57, v56
	s_nop 1
	v_add_f32_dpp v56, v56, v56 quad_perm:[1,0,3,2] row_mask:0xf bank_mask:0xf bound_ctrl:1
	s_nop 1
	v_add_f32_dpp v56, v56, v56 quad_perm:[2,3,0,1] row_mask:0xf bank_mask:0xf bound_ctrl:1
	s_nop 1
	v_add_f32_dpp v56, v56, v56 row_half_mirror row_mask:0xf bank_mask:0xf bound_ctrl:1
	s_nop 1
	v_mov_b32_dpp v57, v56 row_ror:8 row_mask:0xf bank_mask:0xf bound_ctrl:1
	s_and_saveexec_b64 s[18:19], s[16:17]
	v_add_f32_e32 v36, v56, v57
	ds_write_b32 v113, v36
	s_or_b64 exec, exec, s[18:19]
	s_waitcnt lgkmcnt(0)
	s_barrier
	s_add_i32 s1, s0, 1
	s_cmp_eq_u32 s0, 63
	s_cbranch_scc1 .LBB0_1539
	s_cmp_gt_u32 s78, 3
	s_cbranch_scc0 .LBB0_1539
	s_mov_b32 s94, s95
	s_mov_b32 m0, s94
	s_nop 0
	global_load_lds_dwordx4 v[180:181], off
	v_lshl_add_u64 v[180:181], v[180:181], 0, v[208:209]
	s_add_i32 s94, s95, 0x1000
	s_mov_b32 m0, s94
	s_nop 0
	global_load_lds_dwordx4 v[182:183], off
	v_lshl_add_u64 v[182:183], v[182:183], 0, v[210:211]
	s_add_i32 s94, s95, 0x2000
	s_mov_b32 m0, s94
	s_nop 0
	global_load_lds_dwordx4 v[184:185], off
	v_lshl_add_u64 v[184:185], v[184:185], 0, v[212:213]
	s_add_i32 s94, s95, 0x3000
	s_mov_b32 m0, s94
	s_nop 0
	global_load_lds_dwordx4 v[186:187], off
	v_lshl_add_u64 v[186:187], v[186:187], 0, v[214:215]
	s_add_i32 s94, s95, 0x4000
	s_mov_b32 m0, s94
	s_nop 0
	global_load_lds_dwordx4 v[188:189], off
	v_lshl_add_u64 v[188:189], v[188:189], 0, v[216:217]
	s_add_i32 s94, s95, 0x5000
	s_mov_b32 m0, s94
	s_nop 0
	global_load_lds_dwordx4 v[190:191], off
	v_lshl_add_u64 v[190:191], v[190:191], 0, v[218:219]
	s_add_i32 s94, s95, 0x6000
	s_mov_b32 m0, s94
	s_nop 0
	global_load_lds_dwordx4 v[192:193], off
	v_lshl_add_u64 v[192:193], v[192:193], 0, v[220:221]
	s_add_i32 s94, s95, 0x7000
	s_mov_b32 m0, s94
	s_nop 0
	global_load_lds_dwordx4 v[194:195], off
	v_lshl_add_u64 v[194:195], v[194:195], 0, v[222:223]
	s_add_i32 s94, s95, 0x8000
	s_mov_b32 m0, s94
	s_nop 0
	global_load_lds_dwordx4 v[196:197], off
	v_lshl_add_u64 v[196:197], v[196:197], 0, v[224:225]
	s_add_i32 s94, s95, 0x9000
	s_mov_b32 m0, s94
	s_nop 0
	global_load_lds_dwordx4 v[198:199], off
	v_lshl_add_u64 v[198:199], v[198:199], 0, v[226:227]
	s_add_i32 s94, s95, 0xa000
	s_mov_b32 m0, s94
	s_nop 0
	global_load_lds_dwordx4 v[200:201], off
	v_lshl_add_u64 v[200:201], v[200:201], 0, v[228:229]
	s_add_i32 s94, s95, 0xb000
	s_mov_b32 m0, s94
	s_nop 0
	global_load_lds_dwordx4 v[202:203], off
	v_lshl_add_u64 v[202:203], v[202:203], 0, v[230:231]
	s_mov_b64 s[98:99], exec
	s_mov_b64 exec, s[96:97]
	s_add_i32 s94, s95, 0xc000
	s_mov_b32 m0, s94
	s_nop 0
	global_load_lds_dwordx4 v[204:205], off
	s_mov_b64 exec, s[98:99]
	v_lshl_add_u64 v[204:205], v[204:205], 0, v[232:233]
